# mixer work queue: attention and conv items interleaved in pull order (compute-heavy beside memory-heavy) instead of all attention then all conv
# speedup vs baseline: 1.0284x; 1.0054x over previous
; #define LAS __attribute__((address_space(3)))
; __device__ __forceinline__ void phase_mixers(KP p, LAS unsigned char* lds, int l) {
;     unsigned* head = (unsigned*)(p->ws + WS_CTL) + CW_QUEUE + 64 * l;
;     volatile LAS unsigned* qslot = (volatile LAS unsigned*)(lds + LDS_BYTES - 64) + 8;
;     for (;;) {
;         __syncthreads();
;         if (threadIdx.x == 0) qslot[0] = __hip_atomic_fetch_add(head, 1u, __ATOMIC_RELAXED, __HIP_MEMORY_SCOPE_AGENT);
;         __syncthreads();
;         const int it = __builtin_amdgcn_readfirstlane((int)qslot[0]);
;         if (it >= 832) break;
;         if (it < 64) {
;             unsigned char* ws = p->ws;
;             pg8::Gemm g{(const bf16_t*)(ws + WS_XB), (const bf16_t*)(ws + WS_WIN + l * SZ_WIN), SEQ, DIN, DM};
;             pg8::ExtraOrder S{it, DIN / 256 - 1};
;             pg8::EpiH E{(bf16_t*)(ws + WS_HM), (bf16_t*)(ws + WS_HG)};
;             pg8::gemm_phase<GEMM_ALIGN, GEMM_SP2>(lds, g, S, E);
;         }
;         else if (it < 192) sgu_item(p, lds, l, it - 64);
;         else if (it < 448) attn_item(p, lds, l, (it - 192) >> 1, (it - 192) & 1);
;         else if (it < 704) conv_item(p, lds, l, it - 448);
;         else pool_item(p, it - 704);
.LBB0_370:
	s_or_b64 exec, exec, s[40:41]
	v_mov_b32_e32 v0, s53
	s_waitcnt lgkmcnt(0)
	s_barrier
	ds_read_b32 v0, v0
	s_mov_b64 s[40:41], -1
	s_waitcnt lgkmcnt(0)
	v_readfirstlane_b32 s92, v0
	s_cmpk_gt_i32 s92, 0x33f
	s_cbranch_scc1 .LBB0_365
	s_cmpk_lt_i32 s92, 0xc0
	s_cbranch_scc1 .Lq_noremap
	s_cmpk_gt_i32 s92, 0x2bf
	s_cbranch_scc1 .Lq_noremap
	s_sub_i32 s6, s92, 0xc0
	s_lshr_b32 s24, s6, 1
	s_and_b32 s6, s6, 1
	s_lshl_b32 s6, s6, 8
	s_add_i32 s92, s24, s6
	s_addk_i32 s92, 0xc0
.Lq_noremap:
	s_cmp_gt_i32 s92, 63
	s_cbranch_scc0 .LBB0_541
	s_cmpk_gt_u32 s92, 0xbf
	s_cbranch_scc0 .LBB0_517
	s_cmpk_gt_u32 s92, 0x1bf
	s_cbranch_scc0 .LBB0_467
	s_cmpk_gt_u32 s92, 0x2bf
	s_cbranch_scc0 .LBB0_398
	v_mov_b32_e32 v3, v166
	s_lshl_b32 s6, s92, 7
	v_lshlrev_b32_e32 v0, 3, v3
	v_and_b32_e32 v2, 0x3f8, v0
	v_bfe_u32 v0, v0, 8, 2
	v_lshlrev_b32_e64 v80, v0, 2
	v_ashrrev_i32_e32 v0, 2, v3
	v_and_b32_e32 v4, 0xffffffe0, v0
	v_lshlrev_b32_e32 v0, 1, v2
	s_add_i32 s24, s6, 0xfffe9fff
	v_mov_b32_e32 v72, 0
	v_lshl_add_u64 v[66:67], s[36:37], 0, v[0:1]
	v_add_u32_e32 v0, s24, v4
	s_mov_b64 s[40:41], 0
	v_mov_b32_e32 v5, v80
	v_mov_b32_e32 v73, v72
	v_mov_b32_e32 v78, v72
	v_mov_b32_e32 v79, v72
	v_mov_b32_e32 v74, v72
	v_mov_b32_e32 v75, v72
	v_mov_b32_e32 v76, v72
	v_mov_b32_e32 v77, v72
	s_branch .LBB0_377
